# GEMM0/GEMM1 K loops: barrier moved behind MFMA 28 and the next iteration's first six fragment reads issued right after it, under the last four MFMAs
# baseline (speedup 1.0000x reference)
.LBB0_374:
	ds_read_b128 v[114:117], v188 offset:16384
	ds_read_b128 v[118:121], v188 offset:16896
	ds_read_b128 v[156:159], v188 offset:20480
	ds_read_b128 v[160:163], v188 offset:20992
	ds_read_b128 v[122:125], v112
	ds_read_b128 v[126:129], v112 offset:2048
	s_movk_i32 vcc_lo, 7
.Lgq_c:
	s_waitcnt lgkmcnt(1)
	v_mfma_f32_16x16x32_bf16 v[66:69], v[114:117], v[122:125], v[66:69]
	s_setprio 2
	global_load_dwordx4 v[62:65], v216, s[0:1] offset:256
	v_mfma_f32_16x16x32_bf16 v[58:61], v[118:121], v[122:125], v[58:61]
	s_waitcnt vmcnt(8)
	ds_write_b128 v110, v[224:227] offset:32768
	v_mfma_f32_16x16x32_bf16 v[54:57], v[156:159], v[122:125], v[54:57]
	v_mfma_f32_16x16x32_bf16 v[50:53], v[160:163], v[122:125], v[50:53]
	global_load_dwordx4 v[70:73], v217, s[0:1] offset:256
	s_waitcnt lgkmcnt(1)
	v_mfma_f32_16x16x32_bf16 v[46:49], v[114:117], v[126:129], v[46:49]
	ds_read_b128 v[180:183], v112 offset:4096
	ds_read_b128 v[184:187], v112 offset:6144
	v_mfma_f32_16x16x32_bf16 v[42:45], v[118:121], v[126:129], v[42:45]
	s_waitcnt vmcnt(8)
	ds_write_b128 v110, v[228:231] offset:36864
	v_mfma_f32_16x16x32_bf16 v[38:41], v[156:159], v[126:129], v[38:41]
	global_load_dwordx4 v[74:77], v218, s[0:1] offset:256
	v_mfma_f32_16x16x32_bf16 v[34:37], v[160:163], v[126:129], v[34:37]
	s_waitcnt lgkmcnt(2)
	v_mfma_f32_16x16x32_bf16 v[30:33], v[114:117], v[180:183], v[30:33]
	ds_read_b128 v[164:167], v189 offset:16384
	ds_read_b128 v[168:171], v189 offset:16896
	v_mfma_f32_16x16x32_bf16 v[26:29], v[118:121], v[180:183], v[26:29]
	global_load_dwordx4 v[78:81], v219, s[0:1] offset:256
	v_mfma_f32_16x16x32_bf16 v[22:25], v[156:159], v[180:183], v[22:25]
	ds_read_b128 v[172:175], v189 offset:20480
	ds_read_b128 v[176:179], v189 offset:20992
	v_mfma_f32_16x16x32_bf16 v[18:21], v[160:163], v[180:183], v[18:21]
	s_waitcnt vmcnt(9)
	ds_write_b128 v110, v[232:235] offset:40960
	s_waitcnt lgkmcnt(6)
	v_mfma_f32_16x16x32_bf16 v[14:17], v[114:117], v[184:187], v[14:17]
	ds_read_b128 v[122:125], v113
	ds_read_b128 v[126:129], v113 offset:2048
	v_mfma_f32_16x16x32_bf16 v[10:13], v[118:121], v[184:187], v[10:13]
	global_load_dwordx4 v[82:85], v216, s[6:7] offset:256
	v_mfma_f32_16x16x32_bf16 v[6:9], v[156:159], v[184:187], v[6:9]
	s_waitcnt vmcnt(9)
	ds_write_b128 v110, v[236:239] offset:45056
	v_mfma_f32_16x16x32_bf16 v[2:5], v[160:163], v[184:187], v[2:5]
	s_waitcnt lgkmcnt(2)
	v_mfma_f32_16x16x32_bf16 v[66:69], v[164:167], v[122:125], v[66:69]
	global_load_dwordx4 v[86:89], v217, s[6:7] offset:256
	v_mfma_f32_16x16x32_bf16 v[58:61], v[168:171], v[122:125], v[58:61]
	s_waitcnt vmcnt(9)
	ds_write_b128 v190, v[240:243] offset:49168
	v_mfma_f32_16x16x32_bf16 v[54:57], v[172:175], v[122:125], v[54:57]
	v_mfma_f32_16x16x32_bf16 v[50:53], v[176:179], v[122:125], v[50:53]
	global_load_dwordx4 v[90:93], v218, s[6:7] offset:256
	s_waitcnt lgkmcnt(2)
	v_mfma_f32_16x16x32_bf16 v[46:49], v[164:167], v[126:129], v[46:49]
	ds_read_b128 v[180:183], v113 offset:4096
	ds_read_b128 v[184:187], v113 offset:6144
	v_mfma_f32_16x16x32_bf16 v[42:45], v[168:171], v[126:129], v[42:45]
	s_waitcnt vmcnt(9)
	ds_write_b128 v190, v[244:247] offset:53264
	v_mfma_f32_16x16x32_bf16 v[38:41], v[172:175], v[126:129], v[38:41]
	global_load_dwordx4 v[94:97], v219, s[6:7] offset:256
	v_mfma_f32_16x16x32_bf16 v[34:37], v[176:179], v[126:129], v[34:37]
	s_waitcnt lgkmcnt(2)
	v_mfma_f32_16x16x32_bf16 v[30:33], v[164:167], v[180:183], v[30:33]
	s_waitcnt vmcnt(9)
	ds_write_b128 v190, v[248:251] offset:57360
	v_mfma_f32_16x16x32_bf16 v[26:29], v[168:171], v[180:183], v[26:29]
	v_mfma_f32_16x16x32_bf16 v[22:25], v[172:175], v[180:183], v[22:25]
	v_mfma_f32_16x16x32_bf16 v[18:21], v[176:179], v[180:183], v[18:21]
	s_waitcnt vmcnt(8)
	ds_write_b128 v190, v[252:255] offset:61456
	s_setprio 0
	s_waitcnt lgkmcnt(0)
	s_barrier
	ds_read_b128 v[114:117], v188 offset:49168
	ds_read_b128 v[118:121], v188 offset:49680
	ds_read_b128 v[156:159], v188 offset:53264
	ds_read_b128 v[160:163], v188 offset:53776
	ds_read_b128 v[122:125], v112 offset:32768
	ds_read_b128 v[126:129], v112 offset:34816
	s_waitcnt lgkmcnt(9)
	v_mfma_f32_16x16x32_bf16 v[14:17], v[164:167], v[184:187], v[14:17]
	v_mfma_f32_16x16x32_bf16 v[10:13], v[168:171], v[184:187], v[10:13]
	v_mfma_f32_16x16x32_bf16 v[6:9], v[172:175], v[184:187], v[6:9]
	v_mfma_f32_16x16x32_bf16 v[2:5], v[176:179], v[184:187], v[2:5]
	s_add_u32 s0, s0, 0x80
	s_addc_u32 s1, s1, 0
	s_add_u32 s6, s6, 0x80
	s_addc_u32 s7, s7, 0
	s_waitcnt lgkmcnt(1)
	v_mfma_f32_16x16x32_bf16 v[66:69], v[114:117], v[122:125], v[66:69]
	s_setprio 2
	global_load_dwordx4 v[224:227], v216, s[0:1] offset:256
	v_mfma_f32_16x16x32_bf16 v[58:61], v[118:121], v[122:125], v[58:61]
	s_waitcnt vmcnt(8)
	ds_write_b128 v110, v[62:65]
	v_mfma_f32_16x16x32_bf16 v[54:57], v[156:159], v[122:125], v[54:57]
	v_mfma_f32_16x16x32_bf16 v[50:53], v[160:163], v[122:125], v[50:53]
	global_load_dwordx4 v[228:231], v217, s[0:1] offset:256
	s_waitcnt lgkmcnt(1)
	v_mfma_f32_16x16x32_bf16 v[46:49], v[114:117], v[126:129], v[46:49]
	ds_read_b128 v[180:183], v112 offset:36864
	ds_read_b128 v[184:187], v112 offset:38912
	v_mfma_f32_16x16x32_bf16 v[42:45], v[118:121], v[126:129], v[42:45]
	s_waitcnt vmcnt(8)
	ds_write_b128 v110, v[70:73] offset:4096
	v_mfma_f32_16x16x32_bf16 v[38:41], v[156:159], v[126:129], v[38:41]
	global_load_dwordx4 v[232:235], v218, s[0:1] offset:256
	v_mfma_f32_16x16x32_bf16 v[34:37], v[160:163], v[126:129], v[34:37]
	s_waitcnt lgkmcnt(2)
	v_mfma_f32_16x16x32_bf16 v[30:33], v[114:117], v[180:183], v[30:33]
	ds_read_b128 v[164:167], v189 offset:49168
	ds_read_b128 v[168:171], v189 offset:49680
	v_mfma_f32_16x16x32_bf16 v[26:29], v[118:121], v[180:183], v[26:29]
	global_load_dwordx4 v[236:239], v219, s[0:1] offset:256
	v_mfma_f32_16x16x32_bf16 v[22:25], v[156:159], v[180:183], v[22:25]
	ds_read_b128 v[172:175], v189 offset:53264
	ds_read_b128 v[176:179], v189 offset:53776
	v_mfma_f32_16x16x32_bf16 v[18:21], v[160:163], v[180:183], v[18:21]
	s_waitcnt vmcnt(9)
	ds_write_b128 v110, v[74:77] offset:8192
	s_waitcnt lgkmcnt(6)
	v_mfma_f32_16x16x32_bf16 v[14:17], v[114:117], v[184:187], v[14:17]
	ds_read_b128 v[122:125], v113 offset:32768
	ds_read_b128 v[126:129], v113 offset:34816
	v_mfma_f32_16x16x32_bf16 v[10:13], v[118:121], v[184:187], v[10:13]
	global_load_dwordx4 v[240:243], v216, s[6:7] offset:256
	v_mfma_f32_16x16x32_bf16 v[6:9], v[156:159], v[184:187], v[6:9]
	s_waitcnt vmcnt(9)
	ds_write_b128 v110, v[78:81] offset:12288
	v_mfma_f32_16x16x32_bf16 v[2:5], v[160:163], v[184:187], v[2:5]
	s_waitcnt lgkmcnt(2)
	v_mfma_f32_16x16x32_bf16 v[66:69], v[164:167], v[122:125], v[66:69]
	global_load_dwordx4 v[244:247], v217, s[6:7] offset:256
	v_mfma_f32_16x16x32_bf16 v[58:61], v[168:171], v[122:125], v[58:61]
	s_waitcnt vmcnt(9)
	ds_write_b128 v190, v[82:85] offset:16384
	v_mfma_f32_16x16x32_bf16 v[54:57], v[172:175], v[122:125], v[54:57]
	v_mfma_f32_16x16x32_bf16 v[50:53], v[176:179], v[122:125], v[50:53]
	global_load_dwordx4 v[248:251], v218, s[6:7] offset:256
	s_waitcnt lgkmcnt(2)
	v_mfma_f32_16x16x32_bf16 v[46:49], v[164:167], v[126:129], v[46:49]
	ds_read_b128 v[180:183], v113 offset:36864
	ds_read_b128 v[184:187], v113 offset:38912
	v_mfma_f32_16x16x32_bf16 v[42:45], v[168:171], v[126:129], v[42:45]
	s_waitcnt vmcnt(9)
	ds_write_b128 v190, v[86:89] offset:20480
	v_mfma_f32_16x16x32_bf16 v[38:41], v[172:175], v[126:129], v[38:41]
	global_load_dwordx4 v[252:255], v219, s[6:7] offset:256
	v_mfma_f32_16x16x32_bf16 v[34:37], v[176:179], v[126:129], v[34:37]
	s_waitcnt lgkmcnt(2)
	v_mfma_f32_16x16x32_bf16 v[30:33], v[164:167], v[180:183], v[30:33]
	s_waitcnt vmcnt(9)
	ds_write_b128 v190, v[90:93] offset:24576
	v_mfma_f32_16x16x32_bf16 v[26:29], v[168:171], v[180:183], v[26:29]
	v_mfma_f32_16x16x32_bf16 v[22:25], v[172:175], v[180:183], v[22:25]
	v_mfma_f32_16x16x32_bf16 v[18:21], v[176:179], v[180:183], v[18:21]
	s_waitcnt vmcnt(8)
	ds_write_b128 v190, v[94:97] offset:28672
	s_setprio 0
	s_waitcnt lgkmcnt(0)
	s_barrier
	ds_read_b128 v[114:117], v188 offset:16384
	ds_read_b128 v[118:121], v188 offset:16896
	ds_read_b128 v[156:159], v188 offset:20480
	ds_read_b128 v[160:163], v188 offset:20992
	ds_read_b128 v[122:125], v112
	ds_read_b128 v[126:129], v112 offset:2048
	s_waitcnt lgkmcnt(9)
	v_mfma_f32_16x16x32_bf16 v[14:17], v[164:167], v[184:187], v[14:17]
	v_mfma_f32_16x16x32_bf16 v[10:13], v[168:171], v[184:187], v[10:13]
	v_mfma_f32_16x16x32_bf16 v[6:9], v[172:175], v[184:187], v[6:9]
	v_mfma_f32_16x16x32_bf16 v[2:5], v[176:179], v[184:187], v[2:5]
	s_add_u32 s0, s0, 0x80
	s_addc_u32 s1, s1, 0
	s_add_u32 s6, s6, 0x80
	s_addc_u32 s7, s7, 0
	s_sub_i32 vcc_lo, vcc_lo, 1
	s_cmp_lg_u32 vcc_lo, 0
	s_cbranch_scc1 .Lgq_c
	s_waitcnt lgkmcnt(1)
	v_mfma_f32_16x16x32_bf16 v[66:69], v[114:117], v[122:125], v[66:69]
	s_setprio 2
	v_mfma_f32_16x16x32_bf16 v[58:61], v[118:121], v[122:125], v[58:61]
	s_waitcnt vmcnt(7)
	ds_write_b128 v110, v[224:227] offset:32768
	v_mfma_f32_16x16x32_bf16 v[54:57], v[156:159], v[122:125], v[54:57]
	v_mfma_f32_16x16x32_bf16 v[50:53], v[160:163], v[122:125], v[50:53]
	s_waitcnt lgkmcnt(1)
	v_mfma_f32_16x16x32_bf16 v[46:49], v[114:117], v[126:129], v[46:49]
	ds_read_b128 v[180:183], v112 offset:4096
	ds_read_b128 v[184:187], v112 offset:6144
	v_mfma_f32_16x16x32_bf16 v[42:45], v[118:121], v[126:129], v[42:45]
	s_waitcnt vmcnt(6)
	ds_write_b128 v110, v[228:231] offset:36864
	v_mfma_f32_16x16x32_bf16 v[38:41], v[156:159], v[126:129], v[38:41]
	v_mfma_f32_16x16x32_bf16 v[34:37], v[160:163], v[126:129], v[34:37]
	s_waitcnt lgkmcnt(2)
	v_mfma_f32_16x16x32_bf16 v[30:33], v[114:117], v[180:183], v[30:33]
	ds_read_b128 v[164:167], v189 offset:16384
	ds_read_b128 v[168:171], v189 offset:16896
	v_mfma_f32_16x16x32_bf16 v[26:29], v[118:121], v[180:183], v[26:29]
	v_mfma_f32_16x16x32_bf16 v[22:25], v[156:159], v[180:183], v[22:25]
	ds_read_b128 v[172:175], v189 offset:20480
	ds_read_b128 v[176:179], v189 offset:20992
	v_mfma_f32_16x16x32_bf16 v[18:21], v[160:163], v[180:183], v[18:21]
	s_waitcnt vmcnt(5)
	ds_write_b128 v110, v[232:235] offset:40960
	s_waitcnt lgkmcnt(6)
	v_mfma_f32_16x16x32_bf16 v[14:17], v[114:117], v[184:187], v[14:17]
	ds_read_b128 v[122:125], v113
	ds_read_b128 v[126:129], v113 offset:2048
	v_mfma_f32_16x16x32_bf16 v[10:13], v[118:121], v[184:187], v[10:13]
	v_mfma_f32_16x16x32_bf16 v[6:9], v[156:159], v[184:187], v[6:9]
	s_waitcnt vmcnt(4)
	ds_write_b128 v110, v[236:239] offset:45056
	v_mfma_f32_16x16x32_bf16 v[2:5], v[160:163], v[184:187], v[2:5]
	s_waitcnt lgkmcnt(2)
	v_mfma_f32_16x16x32_bf16 v[66:69], v[164:167], v[122:125], v[66:69]
	v_mfma_f32_16x16x32_bf16 v[58:61], v[168:171], v[122:125], v[58:61]
	s_waitcnt vmcnt(3)
	ds_write_b128 v190, v[240:243] offset:49168
	v_mfma_f32_16x16x32_bf16 v[54:57], v[172:175], v[122:125], v[54:57]
	v_mfma_f32_16x16x32_bf16 v[50:53], v[176:179], v[122:125], v[50:53]
	s_waitcnt lgkmcnt(2)
	v_mfma_f32_16x16x32_bf16 v[46:49], v[164:167], v[126:129], v[46:49]
	ds_read_b128 v[180:183], v113 offset:4096
	ds_read_b128 v[184:187], v113 offset:6144
	v_mfma_f32_16x16x32_bf16 v[42:45], v[168:171], v[126:129], v[42:45]
	s_waitcnt vmcnt(2)
	ds_write_b128 v190, v[244:247] offset:53264
	v_mfma_f32_16x16x32_bf16 v[38:41], v[172:175], v[126:129], v[38:41]
	v_mfma_f32_16x16x32_bf16 v[34:37], v[176:179], v[126:129], v[34:37]
	s_waitcnt lgkmcnt(2)
	v_mfma_f32_16x16x32_bf16 v[30:33], v[164:167], v[180:183], v[30:33]
	s_waitcnt vmcnt(1)
	ds_write_b128 v190, v[248:251] offset:57360
	v_mfma_f32_16x16x32_bf16 v[26:29], v[168:171], v[180:183], v[26:29]
	v_mfma_f32_16x16x32_bf16 v[22:25], v[172:175], v[180:183], v[22:25]
	v_mfma_f32_16x16x32_bf16 v[18:21], v[176:179], v[180:183], v[18:21]
	s_waitcnt vmcnt(0)
	ds_write_b128 v190, v[252:255] offset:61456
	s_setprio 0
	s_waitcnt lgkmcnt(0)
	s_barrier
	ds_read_b128 v[114:117], v188 offset:49168
	ds_read_b128 v[118:121], v188 offset:49680
	ds_read_b128 v[156:159], v188 offset:53264
	ds_read_b128 v[160:163], v188 offset:53776
	ds_read_b128 v[122:125], v112 offset:32768
	ds_read_b128 v[126:129], v112 offset:34816
	s_waitcnt lgkmcnt(9)
	v_mfma_f32_16x16x32_bf16 v[14:17], v[164:167], v[184:187], v[14:17]
	v_mfma_f32_16x16x32_bf16 v[10:13], v[168:171], v[184:187], v[10:13]
	v_mfma_f32_16x16x32_bf16 v[6:9], v[172:175], v[184:187], v[6:9]
	v_mfma_f32_16x16x32_bf16 v[2:5], v[176:179], v[184:187], v[2:5]
	s_waitcnt lgkmcnt(1)
	v_mfma_f32_16x16x32_bf16 v[66:69], v[114:117], v[122:125], v[66:69]
	s_setprio 2
	v_mfma_f32_16x16x32_bf16 v[58:61], v[118:121], v[122:125], v[58:61]
	v_mfma_f32_16x16x32_bf16 v[54:57], v[156:159], v[122:125], v[54:57]
	v_mfma_f32_16x16x32_bf16 v[50:53], v[160:163], v[122:125], v[50:53]
	s_waitcnt lgkmcnt(0)
	v_mfma_f32_16x16x32_bf16 v[46:49], v[114:117], v[126:129], v[46:49]
	ds_read_b128 v[180:183], v112 offset:36864
	ds_read_b128 v[184:187], v112 offset:38912
	v_mfma_f32_16x16x32_bf16 v[42:45], v[118:121], v[126:129], v[42:45]
	v_mfma_f32_16x16x32_bf16 v[38:41], v[156:159], v[126:129], v[38:41]
	v_mfma_f32_16x16x32_bf16 v[34:37], v[160:163], v[126:129], v[34:37]
	s_waitcnt lgkmcnt(1)
	v_mfma_f32_16x16x32_bf16 v[30:33], v[114:117], v[180:183], v[30:33]
	ds_read_b128 v[164:167], v189 offset:49168
	ds_read_b128 v[168:171], v189 offset:49680
	v_mfma_f32_16x16x32_bf16 v[26:29], v[118:121], v[180:183], v[26:29]
	v_mfma_f32_16x16x32_bf16 v[22:25], v[156:159], v[180:183], v[22:25]
	ds_read_b128 v[172:175], v189 offset:53264
	ds_read_b128 v[176:179], v189 offset:53776
	v_mfma_f32_16x16x32_bf16 v[18:21], v[160:163], v[180:183], v[18:21]
	s_waitcnt lgkmcnt(4)
	v_mfma_f32_16x16x32_bf16 v[14:17], v[114:117], v[184:187], v[14:17]
	ds_read_b128 v[122:125], v113 offset:32768
	ds_read_b128 v[126:129], v113 offset:34816
	v_mfma_f32_16x16x32_bf16 v[10:13], v[118:121], v[184:187], v[10:13]
	v_mfma_f32_16x16x32_bf16 v[6:9], v[156:159], v[184:187], v[6:9]
	v_mfma_f32_16x16x32_bf16 v[2:5], v[160:163], v[184:187], v[2:5]
	s_waitcnt lgkmcnt(1)
	v_mfma_f32_16x16x32_bf16 v[66:69], v[164:167], v[122:125], v[66:69]
	v_mfma_f32_16x16x32_bf16 v[58:61], v[168:171], v[122:125], v[58:61]
	v_mfma_f32_16x16x32_bf16 v[54:57], v[172:175], v[122:125], v[54:57]
	v_mfma_f32_16x16x32_bf16 v[50:53], v[176:179], v[122:125], v[50:53]
	s_waitcnt lgkmcnt(0)
	v_mfma_f32_16x16x32_bf16 v[46:49], v[164:167], v[126:129], v[46:49]
	ds_read_b128 v[180:183], v113 offset:36864
	ds_read_b128 v[184:187], v113 offset:38912
	v_mfma_f32_16x16x32_bf16 v[42:45], v[168:171], v[126:129], v[42:45]
	v_mfma_f32_16x16x32_bf16 v[38:41], v[172:175], v[126:129], v[38:41]
	v_mfma_f32_16x16x32_bf16 v[34:37], v[176:179], v[126:129], v[34:37]
	s_waitcnt lgkmcnt(1)
	v_mfma_f32_16x16x32_bf16 v[30:33], v[164:167], v[180:183], v[30:33]
	v_mfma_f32_16x16x32_bf16 v[26:29], v[168:171], v[180:183], v[26:29]
	v_mfma_f32_16x16x32_bf16 v[22:25], v[172:175], v[180:183], v[22:25]
	v_mfma_f32_16x16x32_bf16 v[18:21], v[176:179], v[180:183], v[18:21]
	s_waitcnt lgkmcnt(0)
	v_mfma_f32_16x16x32_bf16 v[14:17], v[164:167], v[184:187], v[14:17]
	v_mfma_f32_16x16x32_bf16 v[10:13], v[168:171], v[184:187], v[10:13]
	v_mfma_f32_16x16x32_bf16 v[6:9], v[172:175], v[184:187], v[6:9]
	v_mfma_f32_16x16x32_bf16 v[2:5], v[176:179], v[184:187], v[2:5]
	s_setprio 0
	s_barrier

.LBB0_1386:
	ds_read_b128 v[114:117], v188 offset:16384
	ds_read_b128 v[122:125], v188 offset:16896
	ds_read_b128 v[126:129], v188 offset:20480
	ds_read_b128 v[156:159], v188 offset:20992
	ds_read_b128 v[118:121], v112
	ds_read_b128 v[160:163], v112 offset:2048
	s_movk_i32 vcc_lo, 7
.Lgq_o:
	s_waitcnt lgkmcnt(1)
	v_mfma_f32_16x16x32_bf16 v[94:97], v[114:117], v[118:121], v[94:97]
	s_setprio 2
	global_load_dwordx4 v[2:5], v216, s[10:11] offset:256
	v_mfma_f32_16x16x32_bf16 v[90:93], v[122:125], v[118:121], v[90:93]
	s_waitcnt vmcnt(8)
	ds_write_b128 v108, v[224:227] offset:32768
	v_mfma_f32_16x16x32_bf16 v[86:89], v[126:129], v[118:121], v[86:89]
	v_mfma_f32_16x16x32_bf16 v[82:85], v[156:159], v[118:121], v[82:85]
	global_load_dwordx4 v[6:9], v217, s[10:11] offset:256
	s_waitcnt lgkmcnt(1)
	v_mfma_f32_16x16x32_bf16 v[78:81], v[114:117], v[160:163], v[78:81]
	ds_read_b128 v[180:183], v112 offset:4096
	ds_read_b128 v[184:187], v112 offset:6144
	v_mfma_f32_16x16x32_bf16 v[74:77], v[122:125], v[160:163], v[74:77]
	s_waitcnt vmcnt(8)
	ds_write_b128 v108, v[228:231] offset:36864
	v_mfma_f32_16x16x32_bf16 v[70:73], v[126:129], v[160:163], v[70:73]
	global_load_dwordx4 v[10:13], v218, s[10:11] offset:256
	v_mfma_f32_16x16x32_bf16 v[66:69], v[156:159], v[160:163], v[66:69]
	s_waitcnt lgkmcnt(2)
	v_mfma_f32_16x16x32_bf16 v[62:65], v[114:117], v[180:183], v[62:65]
	ds_read_b128 v[164:167], v189 offset:16384
	ds_read_b128 v[168:171], v189 offset:16896
	v_mfma_f32_16x16x32_bf16 v[58:61], v[122:125], v[180:183], v[58:61]
	global_load_dwordx4 v[14:17], v219, s[10:11] offset:256
	v_mfma_f32_16x16x32_bf16 v[54:57], v[126:129], v[180:183], v[54:57]
	ds_read_b128 v[172:175], v189 offset:20480
	ds_read_b128 v[176:179], v189 offset:20992
	v_mfma_f32_16x16x32_bf16 v[50:53], v[156:159], v[180:183], v[50:53]
	s_waitcnt vmcnt(9)
	ds_write_b128 v108, v[232:235] offset:40960
	s_waitcnt lgkmcnt(6)
	v_mfma_f32_16x16x32_bf16 v[46:49], v[114:117], v[184:187], v[46:49]
	ds_read_b128 v[118:121], v113
	ds_read_b128 v[160:163], v113 offset:2048
	v_mfma_f32_16x16x32_bf16 v[42:45], v[122:125], v[184:187], v[42:45]
	global_load_dwordx4 v[18:21], v216, s[28:29] offset:256
	v_mfma_f32_16x16x32_bf16 v[38:41], v[126:129], v[184:187], v[38:41]
	s_waitcnt vmcnt(9)
	ds_write_b128 v108, v[236:239] offset:45056
	v_mfma_f32_16x16x32_bf16 v[34:37], v[156:159], v[184:187], v[34:37]
	s_waitcnt lgkmcnt(2)
	v_mfma_f32_16x16x32_bf16 v[94:97], v[164:167], v[118:121], v[94:97]
	global_load_dwordx4 v[22:25], v217, s[28:29] offset:256
	v_mfma_f32_16x16x32_bf16 v[90:93], v[168:171], v[118:121], v[90:93]
	s_waitcnt vmcnt(9)
	ds_write_b128 v190, v[240:243] offset:49168
	v_mfma_f32_16x16x32_bf16 v[86:89], v[172:175], v[118:121], v[86:89]
	v_mfma_f32_16x16x32_bf16 v[82:85], v[176:179], v[118:121], v[82:85]
	global_load_dwordx4 v[26:29], v218, s[28:29] offset:256
	s_waitcnt lgkmcnt(2)
	v_mfma_f32_16x16x32_bf16 v[78:81], v[164:167], v[160:163], v[78:81]
	ds_read_b128 v[180:183], v113 offset:4096
	ds_read_b128 v[184:187], v113 offset:6144
	v_mfma_f32_16x16x32_bf16 v[74:77], v[168:171], v[160:163], v[74:77]
	s_waitcnt vmcnt(9)
	ds_write_b128 v190, v[244:247] offset:53264
	v_mfma_f32_16x16x32_bf16 v[70:73], v[172:175], v[160:163], v[70:73]
	global_load_dwordx4 v[30:33], v219, s[28:29] offset:256
	v_mfma_f32_16x16x32_bf16 v[66:69], v[176:179], v[160:163], v[66:69]
	s_waitcnt lgkmcnt(2)
	v_mfma_f32_16x16x32_bf16 v[62:65], v[164:167], v[180:183], v[62:65]
	s_waitcnt vmcnt(9)
	ds_write_b128 v190, v[248:251] offset:57360
	v_mfma_f32_16x16x32_bf16 v[58:61], v[168:171], v[180:183], v[58:61]
	v_mfma_f32_16x16x32_bf16 v[54:57], v[172:175], v[180:183], v[54:57]
	v_mfma_f32_16x16x32_bf16 v[50:53], v[176:179], v[180:183], v[50:53]
	s_waitcnt vmcnt(8)
	ds_write_b128 v190, v[252:255] offset:61456
	s_setprio 0
	s_waitcnt lgkmcnt(0)
	s_barrier
	ds_read_b128 v[114:117], v188 offset:49168
	ds_read_b128 v[122:125], v188 offset:49680
	ds_read_b128 v[126:129], v188 offset:53264
	ds_read_b128 v[156:159], v188 offset:53776
	ds_read_b128 v[118:121], v112 offset:32768
	ds_read_b128 v[160:163], v112 offset:34816
	s_waitcnt lgkmcnt(9)
	v_mfma_f32_16x16x32_bf16 v[46:49], v[164:167], v[184:187], v[46:49]
	v_mfma_f32_16x16x32_bf16 v[42:45], v[168:171], v[184:187], v[42:45]
	v_mfma_f32_16x16x32_bf16 v[38:41], v[172:175], v[184:187], v[38:41]
	v_mfma_f32_16x16x32_bf16 v[34:37], v[176:179], v[184:187], v[34:37]
	s_add_u32 s10, s10, 0x80
	s_addc_u32 s11, s11, 0
	s_add_u32 s28, s28, 0x80
	s_addc_u32 s29, s29, 0
	s_waitcnt lgkmcnt(1)
	v_mfma_f32_16x16x32_bf16 v[94:97], v[114:117], v[118:121], v[94:97]
	s_setprio 2
	global_load_dwordx4 v[224:227], v216, s[10:11] offset:256
	v_mfma_f32_16x16x32_bf16 v[90:93], v[122:125], v[118:121], v[90:93]
	s_waitcnt vmcnt(8)
	ds_write_b128 v108, v[2:5]
	v_mfma_f32_16x16x32_bf16 v[86:89], v[126:129], v[118:121], v[86:89]
	v_mfma_f32_16x16x32_bf16 v[82:85], v[156:159], v[118:121], v[82:85]
	global_load_dwordx4 v[228:231], v217, s[10:11] offset:256
	s_waitcnt lgkmcnt(1)
	v_mfma_f32_16x16x32_bf16 v[78:81], v[114:117], v[160:163], v[78:81]
	ds_read_b128 v[180:183], v112 offset:36864
	ds_read_b128 v[184:187], v112 offset:38912
	v_mfma_f32_16x16x32_bf16 v[74:77], v[122:125], v[160:163], v[74:77]
	s_waitcnt vmcnt(8)
	ds_write_b128 v108, v[6:9] offset:4096
	v_mfma_f32_16x16x32_bf16 v[70:73], v[126:129], v[160:163], v[70:73]
	global_load_dwordx4 v[232:235], v218, s[10:11] offset:256
	v_mfma_f32_16x16x32_bf16 v[66:69], v[156:159], v[160:163], v[66:69]
	s_waitcnt lgkmcnt(2)
	v_mfma_f32_16x16x32_bf16 v[62:65], v[114:117], v[180:183], v[62:65]
	ds_read_b128 v[164:167], v189 offset:49168
	ds_read_b128 v[168:171], v189 offset:49680
	v_mfma_f32_16x16x32_bf16 v[58:61], v[122:125], v[180:183], v[58:61]
	global_load_dwordx4 v[236:239], v219, s[10:11] offset:256
	v_mfma_f32_16x16x32_bf16 v[54:57], v[126:129], v[180:183], v[54:57]
	ds_read_b128 v[172:175], v189 offset:53264
	ds_read_b128 v[176:179], v189 offset:53776
	v_mfma_f32_16x16x32_bf16 v[50:53], v[156:159], v[180:183], v[50:53]
	s_waitcnt vmcnt(9)
	ds_write_b128 v108, v[10:13] offset:8192
	s_waitcnt lgkmcnt(6)
	v_mfma_f32_16x16x32_bf16 v[46:49], v[114:117], v[184:187], v[46:49]
	ds_read_b128 v[118:121], v113 offset:32768
	ds_read_b128 v[160:163], v113 offset:34816
	v_mfma_f32_16x16x32_bf16 v[42:45], v[122:125], v[184:187], v[42:45]
	global_load_dwordx4 v[240:243], v216, s[28:29] offset:256
	v_mfma_f32_16x16x32_bf16 v[38:41], v[126:129], v[184:187], v[38:41]
	s_waitcnt vmcnt(9)
	ds_write_b128 v108, v[14:17] offset:12288
	v_mfma_f32_16x16x32_bf16 v[34:37], v[156:159], v[184:187], v[34:37]
	s_waitcnt lgkmcnt(2)
	v_mfma_f32_16x16x32_bf16 v[94:97], v[164:167], v[118:121], v[94:97]
	global_load_dwordx4 v[244:247], v217, s[28:29] offset:256
	v_mfma_f32_16x16x32_bf16 v[90:93], v[168:171], v[118:121], v[90:93]
	s_waitcnt vmcnt(9)
	ds_write_b128 v190, v[18:21] offset:16384
	v_mfma_f32_16x16x32_bf16 v[86:89], v[172:175], v[118:121], v[86:89]
	v_mfma_f32_16x16x32_bf16 v[82:85], v[176:179], v[118:121], v[82:85]
	global_load_dwordx4 v[248:251], v218, s[28:29] offset:256
	s_waitcnt lgkmcnt(2)
	v_mfma_f32_16x16x32_bf16 v[78:81], v[164:167], v[160:163], v[78:81]
	ds_read_b128 v[180:183], v113 offset:36864
	ds_read_b128 v[184:187], v113 offset:38912
	v_mfma_f32_16x16x32_bf16 v[74:77], v[168:171], v[160:163], v[74:77]
	s_waitcnt vmcnt(9)
	ds_write_b128 v190, v[22:25] offset:20480
	v_mfma_f32_16x16x32_bf16 v[70:73], v[172:175], v[160:163], v[70:73]
	global_load_dwordx4 v[252:255], v219, s[28:29] offset:256
	v_mfma_f32_16x16x32_bf16 v[66:69], v[176:179], v[160:163], v[66:69]
	s_waitcnt lgkmcnt(2)
	v_mfma_f32_16x16x32_bf16 v[62:65], v[164:167], v[180:183], v[62:65]
	s_waitcnt vmcnt(9)
	ds_write_b128 v190, v[26:29] offset:24576
	v_mfma_f32_16x16x32_bf16 v[58:61], v[168:171], v[180:183], v[58:61]
	v_mfma_f32_16x16x32_bf16 v[54:57], v[172:175], v[180:183], v[54:57]
	v_mfma_f32_16x16x32_bf16 v[50:53], v[176:179], v[180:183], v[50:53]
	s_waitcnt vmcnt(8)
	ds_write_b128 v190, v[30:33] offset:28672
	s_setprio 0
	s_waitcnt lgkmcnt(0)
	s_barrier
	ds_read_b128 v[114:117], v188 offset:16384
	ds_read_b128 v[122:125], v188 offset:16896
	ds_read_b128 v[126:129], v188 offset:20480
	ds_read_b128 v[156:159], v188 offset:20992
	ds_read_b128 v[118:121], v112
	ds_read_b128 v[160:163], v112 offset:2048
	s_waitcnt lgkmcnt(9)
	v_mfma_f32_16x16x32_bf16 v[46:49], v[164:167], v[184:187], v[46:49]
	v_mfma_f32_16x16x32_bf16 v[42:45], v[168:171], v[184:187], v[42:45]
	v_mfma_f32_16x16x32_bf16 v[38:41], v[172:175], v[184:187], v[38:41]
	v_mfma_f32_16x16x32_bf16 v[34:37], v[176:179], v[184:187], v[34:37]
	s_add_u32 s10, s10, 0x80
	s_addc_u32 s11, s11, 0
	s_add_u32 s28, s28, 0x80
	s_addc_u32 s29, s29, 0
	s_sub_i32 vcc_lo, vcc_lo, 1
	s_cmp_lg_u32 vcc_lo, 0
	s_cbranch_scc1 .Lgq_o
	s_waitcnt lgkmcnt(1)
	v_mfma_f32_16x16x32_bf16 v[94:97], v[114:117], v[118:121], v[94:97]
	s_setprio 2
	v_mfma_f32_16x16x32_bf16 v[90:93], v[122:125], v[118:121], v[90:93]
	s_waitcnt vmcnt(7)
	ds_write_b128 v108, v[224:227] offset:32768
	v_mfma_f32_16x16x32_bf16 v[86:89], v[126:129], v[118:121], v[86:89]
	v_mfma_f32_16x16x32_bf16 v[82:85], v[156:159], v[118:121], v[82:85]
	s_waitcnt lgkmcnt(1)
	v_mfma_f32_16x16x32_bf16 v[78:81], v[114:117], v[160:163], v[78:81]
	ds_read_b128 v[180:183], v112 offset:4096
	ds_read_b128 v[184:187], v112 offset:6144
	v_mfma_f32_16x16x32_bf16 v[74:77], v[122:125], v[160:163], v[74:77]
	s_waitcnt vmcnt(6)
	ds_write_b128 v108, v[228:231] offset:36864
	v_mfma_f32_16x16x32_bf16 v[70:73], v[126:129], v[160:163], v[70:73]
	v_mfma_f32_16x16x32_bf16 v[66:69], v[156:159], v[160:163], v[66:69]
	s_waitcnt lgkmcnt(2)
	v_mfma_f32_16x16x32_bf16 v[62:65], v[114:117], v[180:183], v[62:65]
	ds_read_b128 v[164:167], v189 offset:16384
	ds_read_b128 v[168:171], v189 offset:16896
	v_mfma_f32_16x16x32_bf16 v[58:61], v[122:125], v[180:183], v[58:61]
	v_mfma_f32_16x16x32_bf16 v[54:57], v[126:129], v[180:183], v[54:57]
	ds_read_b128 v[172:175], v189 offset:20480
	ds_read_b128 v[176:179], v189 offset:20992
	v_mfma_f32_16x16x32_bf16 v[50:53], v[156:159], v[180:183], v[50:53]
	s_waitcnt vmcnt(5)
	ds_write_b128 v108, v[232:235] offset:40960
	s_waitcnt lgkmcnt(6)
	v_mfma_f32_16x16x32_bf16 v[46:49], v[114:117], v[184:187], v[46:49]
	ds_read_b128 v[118:121], v113
	ds_read_b128 v[160:163], v113 offset:2048
	v_mfma_f32_16x16x32_bf16 v[42:45], v[122:125], v[184:187], v[42:45]
	v_mfma_f32_16x16x32_bf16 v[38:41], v[126:129], v[184:187], v[38:41]
	s_waitcnt vmcnt(4)
	ds_write_b128 v108, v[236:239] offset:45056
	v_mfma_f32_16x16x32_bf16 v[34:37], v[156:159], v[184:187], v[34:37]
	s_waitcnt lgkmcnt(2)
	v_mfma_f32_16x16x32_bf16 v[94:97], v[164:167], v[118:121], v[94:97]
	v_mfma_f32_16x16x32_bf16 v[90:93], v[168:171], v[118:121], v[90:93]
	s_waitcnt vmcnt(3)
	ds_write_b128 v190, v[240:243] offset:49168
	v_mfma_f32_16x16x32_bf16 v[86:89], v[172:175], v[118:121], v[86:89]
	v_mfma_f32_16x16x32_bf16 v[82:85], v[176:179], v[118:121], v[82:85]
	s_waitcnt lgkmcnt(2)
	v_mfma_f32_16x16x32_bf16 v[78:81], v[164:167], v[160:163], v[78:81]
	ds_read_b128 v[180:183], v113 offset:4096
	ds_read_b128 v[184:187], v113 offset:6144
	v_mfma_f32_16x16x32_bf16 v[74:77], v[168:171], v[160:163], v[74:77]
	s_waitcnt vmcnt(2)
	ds_write_b128 v190, v[244:247] offset:53264
	v_mfma_f32_16x16x32_bf16 v[70:73], v[172:175], v[160:163], v[70:73]
	v_mfma_f32_16x16x32_bf16 v[66:69], v[176:179], v[160:163], v[66:69]
	s_waitcnt lgkmcnt(2)
	v_mfma_f32_16x16x32_bf16 v[62:65], v[164:167], v[180:183], v[62:65]
	s_waitcnt vmcnt(1)
	ds_write_b128 v190, v[248:251] offset:57360
	v_mfma_f32_16x16x32_bf16 v[58:61], v[168:171], v[180:183], v[58:61]
	v_mfma_f32_16x16x32_bf16 v[54:57], v[172:175], v[180:183], v[54:57]
	v_mfma_f32_16x16x32_bf16 v[50:53], v[176:179], v[180:183], v[50:53]
	s_waitcnt vmcnt(0)
	ds_write_b128 v190, v[252:255] offset:61456
	s_setprio 0
	s_waitcnt lgkmcnt(0)
	s_barrier
	ds_read_b128 v[114:117], v188 offset:49168
	ds_read_b128 v[122:125], v188 offset:49680
	ds_read_b128 v[126:129], v188 offset:53264
	ds_read_b128 v[156:159], v188 offset:53776
	ds_read_b128 v[118:121], v112 offset:32768
	ds_read_b128 v[160:163], v112 offset:34816
	s_waitcnt lgkmcnt(9)
	v_mfma_f32_16x16x32_bf16 v[46:49], v[164:167], v[184:187], v[46:49]
	v_mfma_f32_16x16x32_bf16 v[42:45], v[168:171], v[184:187], v[42:45]
	v_mfma_f32_16x16x32_bf16 v[38:41], v[172:175], v[184:187], v[38:41]
	v_mfma_f32_16x16x32_bf16 v[34:37], v[176:179], v[184:187], v[34:37]
	s_waitcnt lgkmcnt(1)
	v_mfma_f32_16x16x32_bf16 v[94:97], v[114:117], v[118:121], v[94:97]
	s_setprio 2
	v_mfma_f32_16x16x32_bf16 v[90:93], v[122:125], v[118:121], v[90:93]
	v_mfma_f32_16x16x32_bf16 v[86:89], v[126:129], v[118:121], v[86:89]
	v_mfma_f32_16x16x32_bf16 v[82:85], v[156:159], v[118:121], v[82:85]
	s_waitcnt lgkmcnt(0)
	v_mfma_f32_16x16x32_bf16 v[78:81], v[114:117], v[160:163], v[78:81]
	ds_read_b128 v[180:183], v112 offset:36864
	ds_read_b128 v[184:187], v112 offset:38912
	v_mfma_f32_16x16x32_bf16 v[74:77], v[122:125], v[160:163], v[74:77]
	v_mfma_f32_16x16x32_bf16 v[70:73], v[126:129], v[160:163], v[70:73]
	v_mfma_f32_16x16x32_bf16 v[66:69], v[156:159], v[160:163], v[66:69]
	s_waitcnt lgkmcnt(1)
	v_mfma_f32_16x16x32_bf16 v[62:65], v[114:117], v[180:183], v[62:65]
	ds_read_b128 v[164:167], v189 offset:49168
	ds_read_b128 v[168:171], v189 offset:49680
	v_mfma_f32_16x16x32_bf16 v[58:61], v[122:125], v[180:183], v[58:61]
	v_mfma_f32_16x16x32_bf16 v[54:57], v[126:129], v[180:183], v[54:57]
	ds_read_b128 v[172:175], v189 offset:53264
	ds_read_b128 v[176:179], v189 offset:53776
	v_mfma_f32_16x16x32_bf16 v[50:53], v[156:159], v[180:183], v[50:53]
	s_waitcnt lgkmcnt(4)
	v_mfma_f32_16x16x32_bf16 v[46:49], v[114:117], v[184:187], v[46:49]
	ds_read_b128 v[118:121], v113 offset:32768
	ds_read_b128 v[160:163], v113 offset:34816
	v_mfma_f32_16x16x32_bf16 v[42:45], v[122:125], v[184:187], v[42:45]
	v_mfma_f32_16x16x32_bf16 v[38:41], v[126:129], v[184:187], v[38:41]
	v_mfma_f32_16x16x32_bf16 v[34:37], v[156:159], v[184:187], v[34:37]
	s_waitcnt lgkmcnt(1)
	v_mfma_f32_16x16x32_bf16 v[94:97], v[164:167], v[118:121], v[94:97]
	v_mfma_f32_16x16x32_bf16 v[90:93], v[168:171], v[118:121], v[90:93]
	v_mfma_f32_16x16x32_bf16 v[86:89], v[172:175], v[118:121], v[86:89]
	v_mfma_f32_16x16x32_bf16 v[82:85], v[176:179], v[118:121], v[82:85]
	s_waitcnt lgkmcnt(0)
	v_mfma_f32_16x16x32_bf16 v[78:81], v[164:167], v[160:163], v[78:81]
	ds_read_b128 v[180:183], v113 offset:36864
	ds_read_b128 v[184:187], v113 offset:38912
	v_mfma_f32_16x16x32_bf16 v[74:77], v[168:171], v[160:163], v[74:77]
	v_mfma_f32_16x16x32_bf16 v[70:73], v[172:175], v[160:163], v[70:73]
	v_mfma_f32_16x16x32_bf16 v[66:69], v[176:179], v[160:163], v[66:69]
	s_waitcnt lgkmcnt(1)
	v_mfma_f32_16x16x32_bf16 v[62:65], v[164:167], v[180:183], v[62:65]
	v_mfma_f32_16x16x32_bf16 v[58:61], v[168:171], v[180:183], v[58:61]
	v_mfma_f32_16x16x32_bf16 v[54:57], v[172:175], v[180:183], v[54:57]
	v_mfma_f32_16x16x32_bf16 v[50:53], v[176:179], v[180:183], v[50:53]
	s_waitcnt lgkmcnt(0)
	v_mfma_f32_16x16x32_bf16 v[46:49], v[164:167], v[184:187], v[46:49]
	v_mfma_f32_16x16x32_bf16 v[42:45], v[168:171], v[184:187], v[42:45]
	v_mfma_f32_16x16x32_bf16 v[38:41], v[172:175], v[184:187], v[38:41]
	v_mfma_f32_16x16x32_bf16 v[34:37], v[176:179], v[184:187], v[34:37]
	s_setprio 0
	s_barrier
	s_branch .LBB0_1383
